# attention: unit-prologue max|q|^2 via permlane32 swap + DPP row max + readlane (was six ds_bpermute round trips); row-max code without canonicalising self-max
# speedup vs baseline: 1.0019x; 1.0005x over previous
.LBB0_137:
	s_or_b64 exec, exec, s[12:13]
	s_ashr_i32 s16, s20, 6
	s_sub_i32 s19, 15, s16
	s_lshr_b32 s15, s18, 4
	s_lshl_b32 s17, s15, 12
	s_lshl_b32 s14, s19, 8
	s_add_u32 s2, s17, s14
	s_addc_u32 s3, 0, 0
	v_and_b32_e32 v30, 0xffffffe0, v202
	v_lshrrev_b32_e32 v31, 3, v244
	v_or_b32_e32 v30, v30, v31
	v_mov_b32_e32 v31, 0
	v_lshl_add_u64 v[10:11], s[2:3], 0, v[30:31]
	v_readlane_b32 s2, v252, 23
	v_lshlrev_b64 v[10:11], 11, v[10:11]
	v_readlane_b32 s3, v252, 24
	s_mov_b32 s13, s79
	v_and_b32_e32 v30, 7, v244
	v_lshl_add_u64 v[10:11], s[2:3], 0, v[10:11]
	s_lshl_b32 s2, s20, 6
	s_and_b32 s2, s2, 0x3c0
	s_lshl_b32 s12, s2, 1
	v_lshlrev_b32_e32 v30, 4, v30
	v_lshl_add_u64 v[10:11], v[10:11], 0, s[12:13]
	v_readfirstlane_b32 s32, v200
	v_lshl_add_u64 v[10:11], v[10:11], 0, v[30:31]
	s_mov_b64 s[100:101], 0x4000
	s_lshr_b32 s32, s32, 6
	s_lshl_b32 s32, s32, 12
	s_add_i32 m0, s32, 0xc800
	s_nop 0
	global_load_lds_dwordx4 v[10:11], off
	v_lshl_add_u64 v[10:11], v[10:11], 0, s[100:101]
	s_add_i32 m0, s32, 0xcc00
	s_nop 0
	global_load_lds_dwordx4 v[10:11], off
	v_lshl_add_u64 v[10:11], v[10:11], 0, s[100:101]
	s_add_i32 m0, s32, 0xd000
	s_nop 0
	global_load_lds_dwordx4 v[10:11], off
	v_lshl_add_u64 v[10:11], v[10:11], 0, s[100:101]
	s_add_i32 m0, s32, 0xd400
	s_nop 0
	global_load_lds_dwordx4 v[10:11], off
	s_lshl_b32 s2, s18, 3
	v_mov_b32_e32 v30, s2
	global_load_dwordx2 v[34:35], v30, s[10:11]
	v_cmp_lt_i32_e64 s[2:3], v237, v231
	s_waitcnt vmcnt(0)
	v_lshlrev_b32_e32 v30, 7, v202
	v_add_u32_e32 v30, v30, v192
	ds_read_b128 v[14:17], v30 offset:51200
	ds_read_b128 v[18:21], v30 offset:51232
	ds_read_b128 v[22:25], v30 offset:51264
	ds_read_b128 v[26:29], v30 offset:51296
	s_waitcnt lgkmcnt(0)
	v_and_b32_e32 v31, 0xffff0000, v14
	v_lshlrev_b32_e32 v30, 16, v14
	v_mul_f32_e32 v31, v31, v31
	v_fmac_f32_e32 v31, v30, v30
	v_and_b32_e32 v13, 0xffff0000, v15
	v_lshlrev_b32_e32 v30, 16, v15
	v_mul_f32_e32 v13, v13, v13
	v_fmac_f32_e32 v13, v30, v30
	v_add_f32_e32 v9, v31, v13
	v_and_b32_e32 v13, 0xffff0000, v16
	v_lshlrev_b32_e32 v30, 16, v16
	v_mul_f32_e32 v13, v13, v13
	v_fmac_f32_e32 v13, v30, v30
	v_add_f32_e32 v9, v13, v9
	v_and_b32_e32 v13, 0xffff0000, v17
	v_lshlrev_b32_e32 v30, 16, v17
	v_mul_f32_e32 v13, v13, v13
	v_fmac_f32_e32 v13, v30, v30
	v_add_f32_e32 v9, v13, v9
	v_and_b32_e32 v13, 0xffff0000, v18
	v_lshlrev_b32_e32 v30, 16, v18
	v_mul_f32_e32 v13, v13, v13
	v_fmac_f32_e32 v13, v30, v30
	v_add_f32_e32 v9, v13, v9
	v_and_b32_e32 v13, 0xffff0000, v19
	v_lshlrev_b32_e32 v30, 16, v19
	v_mul_f32_e32 v13, v13, v13
	v_fmac_f32_e32 v13, v30, v30
	v_add_f32_e32 v9, v13, v9
	v_and_b32_e32 v13, 0xffff0000, v20
	v_lshlrev_b32_e32 v30, 16, v20
	v_mul_f32_e32 v13, v13, v13
	v_fmac_f32_e32 v13, v30, v30
	v_add_f32_e32 v9, v13, v9
	v_and_b32_e32 v13, 0xffff0000, v21
	v_lshlrev_b32_e32 v30, 16, v21
	v_mul_f32_e32 v13, v13, v13
	v_fmac_f32_e32 v13, v30, v30
	v_add_f32_e32 v9, v13, v9
	v_and_b32_e32 v13, 0xffff0000, v22
	v_lshlrev_b32_e32 v30, 16, v22
	v_mul_f32_e32 v13, v13, v13
	v_fmac_f32_e32 v13, v30, v30
	v_add_f32_e32 v9, v13, v9
	v_and_b32_e32 v13, 0xffff0000, v23
	v_lshlrev_b32_e32 v30, 16, v23
	v_mul_f32_e32 v13, v13, v13
	v_fmac_f32_e32 v13, v30, v30
	v_add_f32_e32 v9, v13, v9
	v_and_b32_e32 v13, 0xffff0000, v24
	v_lshlrev_b32_e32 v30, 16, v24
	v_mul_f32_e32 v13, v13, v13
	v_fmac_f32_e32 v13, v30, v30
	v_add_f32_e32 v9, v13, v9
	v_and_b32_e32 v13, 0xffff0000, v25
	v_lshlrev_b32_e32 v30, 16, v25
	v_mul_f32_e32 v13, v13, v13
	v_fmac_f32_e32 v13, v30, v30
	v_add_f32_e32 v9, v13, v9
	v_and_b32_e32 v13, 0xffff0000, v26
	v_lshlrev_b32_e32 v30, 16, v26
	v_mul_f32_e32 v13, v13, v13
	v_fmac_f32_e32 v13, v30, v30
	v_add_f32_e32 v9, v13, v9
	v_and_b32_e32 v13, 0xffff0000, v27
	v_lshlrev_b32_e32 v30, 16, v27
	v_mul_f32_e32 v13, v13, v13
	v_fmac_f32_e32 v13, v30, v30
	v_add_f32_e32 v9, v13, v9
	v_and_b32_e32 v13, 0xffff0000, v28
	v_lshlrev_b32_e32 v30, 16, v28
	v_mul_f32_e32 v13, v13, v13
	v_fmac_f32_e32 v13, v30, v30
	v_add_f32_e32 v9, v13, v9
	v_and_b32_e32 v13, 0xffff0000, v29
	v_lshlrev_b32_e32 v30, 16, v29
	v_mul_f32_e32 v13, v13, v13
	v_fmac_f32_e32 v13, v30, v30
	v_add_f32_e32 v9, v13, v9
	s_waitcnt lgkmcnt(0)
	v_mov_b32_e32 v10, v9
	s_nop 1
	v_permlane32_swap_b32_e32 v9, v10
	v_add_f32_e32 v9, v9, v10
	s_nop 1
	v_max_f32_dpp v9, v9, v9 quad_perm:[1,0,3,2] row_mask:0xf bank_mask:0xf
	s_nop 1
	v_max_f32_dpp v9, v9, v9 quad_perm:[2,3,0,1] row_mask:0xf bank_mask:0xf
	s_nop 1
	v_max_f32_dpp v9, v9, v9 row_half_mirror row_mask:0xf bank_mask:0xf
	s_nop 1
	v_max_f32_dpp v9, v9, v9 row_mirror row_mask:0xf bank_mask:0xf
	s_nop 1
	v_max_f32_dpp v9, v9, v9 row_bcast:15 row_mask:0xa bank_mask:0xf
	s_nop 0
	v_readlane_b32 s32, v9, 31
	s_nop 1
	v_mov_b32_e32 v9, s32
	v_mov_b32_e32 v10, s32
	s_and_saveexec_b64 s[2:3], s[6:7]
	s_cbranch_execnz .LBB0_162
	s_or_b64 exec, exec, s[2:3]
	s_and_saveexec_b64 s[2:3], s[4:5]
	s_cbranch_execnz .LBB0_163

.LBB0_148:
	v_add_u32_e32 v168, s6, v221
	ds_read_b64_tr_b16 v[164:165], v168 offset:24576
	ds_read_b64_tr_b16 v[166:167], v168 offset:25088
	v_mfma_f32_32x32x16_bf16 v[64:79], v[156:159], v[116:119], v[64:79]
	v_add_f32_e32 v104, v80, v81
	v_add_f32_e32 v104, v82, v104
	v_add_f32_e32 v104, v83, v104
	v_add_f32_e32 v104, v84, v104
	v_add_f32_e32 v104, v85, v104
	v_cvt_pk_bf16_f32 v124, v80, v81
	v_cvt_pk_bf16_f32 v125, v82, v83
	ds_read_b64_tr_b16 v[160:161], v168 offset:28672
	ds_read_b64_tr_b16 v[162:163], v168 offset:29184
	v_mfma_f32_32x32x16_bf16 v[48:63], v[152:155], v[116:119], v[48:63]
	v_add_f32_e32 v80, v86, v104
	v_add_f32_e32 v80, v87, v80
	v_add_f32_e32 v80, v88, v80
	v_add_f32_e32 v80, v89, v80
	v_cvt_pk_bf16_f32 v126, v84, v85
	v_cvt_pk_bf16_f32 v127, v86, v87
	ds_read_b64_tr_b16 v[152:153], v168 offset:25600
	ds_read_b64_tr_b16 v[154:155], v168 offset:26112
	v_mfma_f32_32x32x16_bf16 v[64:79], v[148:151], v[108:111], v[64:79]
	v_add_f32_e32 v80, v90, v80
	v_add_f32_e32 v80, v91, v80
	v_add_f32_e32 v80, v92, v80
	v_add_f32_e32 v80, v93, v80
	v_cvt_pk_bf16_f32 v120, v88, v89
	v_cvt_pk_bf16_f32 v121, v90, v91
	ds_read_b64_tr_b16 v[148:149], v168 offset:29696
	ds_read_b64_tr_b16 v[150:151], v168 offset:30208
	v_mfma_f32_32x32x16_bf16 v[48:63], v[144:147], v[108:111], v[48:63]
	v_add_f32_e32 v80, v94, v80
	v_add_f32_e32 v80, v95, v80
	v_add_f32_e32 v80, v32, v80
	v_add_f32_e32 v80, v33, v80
	v_cvt_pk_bf16_f32 v122, v92, v93
	v_cvt_pk_bf16_f32 v123, v94, v95
	ds_read_b64_tr_b16 v[156:157], v168 offset:26624
	ds_read_b64_tr_b16 v[158:159], v168 offset:27136
	v_mfma_f32_32x32x16_bf16 v[64:79], v[140:143], v[100:103], v[64:79]
	v_add_f32_e32 v80, v34, v80
	v_add_f32_e32 v80, v35, v80
	v_add_f32_e32 v80, v36, v80
	v_add_f32_e32 v80, v37, v80
	v_cvt_pk_bf16_f32 v112, v32, v33
	v_cvt_pk_bf16_f32 v113, v34, v35
	ds_read_b64_tr_b16 v[144:145], v168 offset:30720
	ds_read_b64_tr_b16 v[146:147], v168 offset:31232
	v_mfma_f32_32x32x16_bf16 v[48:63], v[132:135], v[100:103], v[48:63]
	v_add_f32_e32 v32, v38, v80
	v_add_f32_e32 v32, v39, v32
	v_add_f32_e32 v32, v40, v32
	v_add_f32_e32 v32, v41, v32
	v_cvt_pk_bf16_f32 v114, v36, v37
	v_cvt_pk_bf16_f32 v115, v38, v39
	ds_read_b64_tr_b16 v[140:141], v168 offset:27648
	ds_read_b64_tr_b16 v[142:143], v168 offset:28160
	v_mfma_f32_32x32x16_bf16 v[64:79], v[136:139], v[96:99], v[64:79]
	v_add_f32_e32 v32, v42, v32
	v_add_f32_e32 v32, v43, v32
	v_add_f32_e32 v32, v44, v32
	v_add_f32_e32 v32, v45, v32
	v_cvt_pk_bf16_f32 v104, v40, v41
	v_cvt_pk_bf16_f32 v105, v42, v43
	ds_read_b64_tr_b16 v[132:133], v168 offset:31744
	ds_read_b64_tr_b16 v[134:135], v168 offset:32256
	v_mfma_f32_32x32x16_bf16 v[48:63], v[128:131], v[96:99], v[48:63]
	v_add_f32_e32 v32, v46, v32
	v_add_f32_e32 v32, v47, v32
	v_add_f32_e32 v34, 0, v32
	v_cvt_pk_bf16_f32 v106, v44, v45
	v_cvt_pk_bf16_f32 v107, v46, v47
	v_lshl_add_u64 v[32:33], v[178:179], 0, s[90:91]
	s_add_i32 s6, s41, s18
	s_mov_b32 m0, s6
	s_nop 0
	global_load_lds_dwordx4 v[32:33], off
	v_lshl_add_u64 v[32:33], v[176:177], 0, s[90:91]
	s_add_i32 s6, s28, s19
	s_mov_b32 m0, s6
	s_nop 0
	global_load_lds_dwordx4 v[32:33], off
	v_max_f32_e32 v32, v64, v65
	v_max3_f32 v33, v66, v67, v49
	v_max3_f32 v32, v32, v48, v50
	v_max3_f32 v32, v32, v51, v68
	v_max3_f32 v33, v33, v70, v71
	v_max3_f32 v32, v32, v69, v52
	v_max3_f32 v33, v33, v54, v55
	v_max3_f32 v32, v32, v53, v72
	v_max3_f32 v33, v33, v74, v75
	v_max3_f32 v32, v32, v73, v56
	v_max3_f32 v33, v33, v58, v59
	v_max3_f32 v32, v32, v57, v76
	v_max3_f32 v33, v33, v78, v79
	v_max3_f32 v32, v32, v77, v60
	v_max3_f32 v33, v33, v62, v63
	v_max3_f32 v32, v32, v61, v33
	v_mov_b32_e32 v33, v32
	s_nop 1
	v_permlane32_swap_b32_e32 v32, v33
	v_max_f32_e32 v32, v32, v33
	v_cmp_lt_f32_e32 vcc, s47, v32
	s_cmp_lg_u64 vcc, 0
	v_add_f32_e32 v181, v222, v34
	s_cselect_b64 s[6:7], -1, 0
	s_cbranch_vccnz .LBB0_156

.LBB0_151:
	s_add_i32 s6, s28, 0x2000
	s_cmpk_lg_i32 s28, 0x4000
	s_cselect_b32 s22, s6, 0
	v_add_u32_e32 v182, s41, v221
	ds_read_b64_tr_b16 v[144:145], v182 offset:24576
	ds_read_b64_tr_b16 v[146:147], v182 offset:25088
	v_mfma_f32_32x32x16_bf16 v[80:95], v[168:171], v[116:119], v[80:95]
	v_add_f32_e32 v104, v64, v65
	v_add_f32_e32 v104, v66, v104
	v_add_f32_e32 v104, v67, v104
	v_add_f32_e32 v104, v68, v104
	v_add_f32_e32 v104, v69, v104
	v_cvt_pk_bf16_f32 v124, v64, v65
	v_cvt_pk_bf16_f32 v125, v66, v67
	ds_read_b64_tr_b16 v[140:141], v182 offset:28672
	ds_read_b64_tr_b16 v[142:143], v182 offset:29184
	v_mfma_f32_32x32x16_bf16 v[32:47], v[128:131], v[116:119], v[32:47]
	v_add_f32_e32 v64, v70, v104
	v_add_f32_e32 v64, v71, v64
	v_add_f32_e32 v64, v72, v64
	v_add_f32_e32 v64, v73, v64
	v_cvt_pk_bf16_f32 v126, v68, v69
	v_cvt_pk_bf16_f32 v127, v70, v71
	ds_read_b64_tr_b16 v[132:133], v182 offset:25600
	ds_read_b64_tr_b16 v[134:135], v182 offset:26112
	v_mfma_f32_32x32x16_bf16 v[80:95], v[164:167], v[108:111], v[80:95]
	v_add_f32_e32 v64, v74, v64
	v_add_f32_e32 v64, v75, v64
	v_add_f32_e32 v64, v76, v64
	v_add_f32_e32 v64, v77, v64
	v_cvt_pk_bf16_f32 v120, v72, v73
	v_cvt_pk_bf16_f32 v121, v74, v75
	ds_read_b64_tr_b16 v[128:129], v182 offset:29696
	ds_read_b64_tr_b16 v[130:131], v182 offset:30208
	v_mfma_f32_32x32x16_bf16 v[32:47], v[152:155], v[108:111], v[32:47]
	v_add_f32_e32 v64, v78, v64
	v_add_f32_e32 v64, v79, v64
	v_add_f32_e32 v64, v48, v64
	v_add_f32_e32 v64, v49, v64
	v_cvt_pk_bf16_f32 v122, v76, v77
	v_cvt_pk_bf16_f32 v123, v78, v79
	ds_read_b64_tr_b16 v[172:173], v182 offset:26624
	ds_read_b64_tr_b16 v[174:175], v182 offset:27136
	v_mfma_f32_32x32x16_bf16 v[80:95], v[160:163], v[100:103], v[80:95]
	v_add_f32_e32 v64, v50, v64
	v_add_f32_e32 v64, v51, v64
	v_add_f32_e32 v64, v52, v64
	v_add_f32_e32 v64, v53, v64
	v_cvt_pk_bf16_f32 v112, v48, v49
	v_cvt_pk_bf16_f32 v113, v50, v51
	ds_read_b64_tr_b16 v[168:169], v182 offset:30720
	ds_read_b64_tr_b16 v[170:171], v182 offset:31232
	v_mfma_f32_32x32x16_bf16 v[32:47], v[148:151], v[100:103], v[32:47]
	v_add_f32_e32 v48, v54, v64
	v_add_f32_e32 v48, v55, v48
	v_add_f32_e32 v48, v56, v48
	v_add_f32_e32 v48, v57, v48
	v_cvt_pk_bf16_f32 v114, v52, v53
	v_cvt_pk_bf16_f32 v115, v54, v55
	ds_read_b64_tr_b16 v[164:165], v182 offset:27648
	ds_read_b64_tr_b16 v[166:167], v182 offset:28160
	v_mfma_f32_32x32x16_bf16 v[80:95], v[156:159], v[96:99], v[80:95]
	v_add_f32_e32 v48, v58, v48
	v_add_f32_e32 v48, v59, v48
	v_add_f32_e32 v48, v60, v48
	v_add_f32_e32 v48, v61, v48
	v_cvt_pk_bf16_f32 v104, v56, v57
	v_cvt_pk_bf16_f32 v105, v58, v59
	ds_read_b64_tr_b16 v[160:161], v182 offset:31744
	ds_read_b64_tr_b16 v[162:163], v182 offset:32256
	v_mfma_f32_32x32x16_bf16 v[32:47], v[136:139], v[96:99], v[32:47]
	v_add_f32_e32 v48, v62, v48
	v_add_f32_e32 v48, v63, v48
	v_add_f32_e32 v48, 0, v48
	v_cvt_pk_bf16_f32 v106, v60, v61
	v_cvt_pk_bf16_f32 v107, v62, v63
	v_max_f32_e32 v49, v80, v81
	s_nop 3
	v_max3_f32 v50, v82, v83, v33
	v_max3_f32 v49, v49, v32, v34
	v_max3_f32 v49, v49, v35, v84
	v_max3_f32 v50, v50, v86, v87
	v_max3_f32 v49, v49, v85, v36
	v_max3_f32 v50, v50, v38, v39
	v_max3_f32 v49, v49, v37, v88
	v_max3_f32 v50, v50, v90, v91
	v_max3_f32 v49, v49, v89, v40
	v_max3_f32 v50, v50, v42, v43
	v_max3_f32 v49, v49, v41, v92
	v_max3_f32 v50, v50, v94, v95
	v_max3_f32 v49, v49, v93, v44
	v_max3_f32 v50, v50, v46, v47
	v_add_f32_e32 v222, v181, v48
	v_max3_f32 v48, v49, v45, v50
	v_mov_b32_e32 v49, v48
	s_nop 1
	v_permlane32_swap_b32_e32 v48, v49
	v_max_f32_e32 v49, v49, v49
	v_max_f32_e32 v48, v48, v48
	s_add_i32 s6, s28, s18
	s_mov_b32 m0, s6
	s_nop 0
	global_load_lds_dwordx4 v[178:179], off
	v_max_f32_e32 v48, v48, v49
	s_add_i32 s6, s22, s19
	s_mov_b32 m0, s6
	s_nop 0
	global_load_lds_dwordx4 v[176:177], off
	v_cmp_lt_f32_e32 vcc, s47, v48
	s_cmp_lg_u64 vcc, 0
	s_cselect_b64 s[6:7], -1, 0
	s_cbranch_vccnz .LBB0_159

.LBB0_167:
	v_add_u32_e32 v164, s24, v221
	ds_read_b64_tr_b16 v[160:161], v164 offset:24576
	ds_read_b64_tr_b16 v[162:163], v164 offset:25088
	v_mfma_f32_32x32x16_bf16 v[64:79], v[156:159], v[116:119], v[64:79]
	v_add_f32_e32 v104, v80, v81
	v_add_f32_e32 v104, v82, v104
	v_add_f32_e32 v104, v83, v104
	v_add_f32_e32 v104, v84, v104
	v_add_f32_e32 v104, v85, v104
	v_cvt_pk_bf16_f32 v124, v80, v81
	v_cvt_pk_bf16_f32 v125, v82, v83
	ds_read_b64_tr_b16 v[156:157], v164 offset:28672
	ds_read_b64_tr_b16 v[158:159], v164 offset:29184
	v_mfma_f32_32x32x16_bf16 v[48:63], v[152:155], v[116:119], v[48:63]
	v_add_f32_e32 v104, v86, v104
	v_add_f32_e32 v104, v87, v104
	v_add_f32_e32 v104, v88, v104
	v_add_f32_e32 v104, v89, v104
	v_cvt_pk_bf16_f32 v126, v84, v85
	v_cvt_pk_bf16_f32 v127, v86, v87
	ds_read_b64_tr_b16 v[152:153], v164 offset:25600
	ds_read_b64_tr_b16 v[154:155], v164 offset:26112
	v_mfma_f32_32x32x16_bf16 v[64:79], v[148:151], v[108:111], v[64:79]
	v_add_f32_e32 v104, v90, v104
	v_add_f32_e32 v104, v91, v104
	v_add_f32_e32 v104, v92, v104
	v_add_f32_e32 v104, v93, v104
	v_cvt_pk_bf16_f32 v120, v88, v89
	v_cvt_pk_bf16_f32 v121, v90, v91
	ds_read_b64_tr_b16 v[148:149], v164 offset:29696
	ds_read_b64_tr_b16 v[150:151], v164 offset:30208
	v_mfma_f32_32x32x16_bf16 v[48:63], v[144:147], v[108:111], v[48:63]
	v_add_f32_e32 v104, v94, v104
	v_add_f32_e32 v104, v95, v104
	v_add_f32_e32 v104, v32, v104
	v_add_f32_e32 v104, v33, v104
	v_cvt_pk_bf16_f32 v122, v92, v93
	v_cvt_pk_bf16_f32 v123, v94, v95
	ds_read_b64_tr_b16 v[144:145], v164 offset:26624
	ds_read_b64_tr_b16 v[146:147], v164 offset:27136
	v_mfma_f32_32x32x16_bf16 v[64:79], v[140:143], v[100:103], v[64:79]
	v_add_f32_e32 v104, v34, v104
	v_add_f32_e32 v104, v35, v104
	v_add_f32_e32 v104, v36, v104
	v_add_f32_e32 v104, v37, v104
	v_cvt_pk_bf16_f32 v112, v32, v33
	v_cvt_pk_bf16_f32 v113, v34, v35
	ds_read_b64_tr_b16 v[116:117], v164 offset:30720
	ds_read_b64_tr_b16 v[118:119], v164 offset:31232
	v_mfma_f32_32x32x16_bf16 v[48:63], v[132:135], v[100:103], v[48:63]
	v_add_f32_e32 v100, v38, v104
	v_add_f32_e32 v100, v39, v100
	v_add_f32_e32 v100, v40, v100
	v_add_f32_e32 v100, v41, v100
	v_cvt_pk_bf16_f32 v114, v36, v37
	v_cvt_pk_bf16_f32 v115, v38, v39
	ds_read_b64_tr_b16 v[108:109], v164 offset:27648
	ds_read_b64_tr_b16 v[110:111], v164 offset:28160
	v_mfma_f32_32x32x16_bf16 v[64:79], v[136:139], v[96:99], v[64:79]
	v_add_f32_e32 v100, v42, v100
	v_add_f32_e32 v100, v43, v100
	v_add_f32_e32 v100, v44, v100
	v_add_f32_e32 v132, v45, v100
	v_cvt_pk_bf16_f32 v104, v40, v41
	v_cvt_pk_bf16_f32 v105, v42, v43
	ds_read_b64_tr_b16 v[100:101], v164 offset:31744
	ds_read_b64_tr_b16 v[102:103], v164 offset:32256
	v_mfma_f32_32x32x16_bf16 v[48:63], v[128:131], v[96:99], v[48:63]
	v_add_f32_e32 v96, v46, v132
	v_add_f32_e32 v96, v47, v96
	v_add_f32_e32 v96, 0, v96
	v_cvt_pk_bf16_f32 v106, v44, v45
	v_cvt_pk_bf16_f32 v107, v46, v47
	v_or_b32_e32 v98, 0xe0, v218
	v_or_b32_e32 v97, 0xc0, v218
	v_cmp_le_i32_e32 vcc, v98, v219
	v_add_f32_e32 v96, v222, v96
	s_nop 2
	v_cndmask_b32_e32 v48, v238, v48, vcc
	v_cmp_lt_i32_e32 vcc, v97, v219
	s_nop 1
	v_cndmask_b32_e32 v65, v238, v65, vcc
	v_cmp_le_i32_e32 vcc, v97, v219
	v_or_b32_e32 v97, 0xe1, v218
	s_nop 0
	v_cndmask_b32_e32 v64, v238, v64, vcc
	v_cmp_le_i32_e32 vcc, v97, v219
	v_or_b32_e32 v97, 0xc2, v218
	v_max_f32_e32 v98, v64, v64
	v_cndmask_b32_e32 v49, v238, v49, vcc
	v_cmp_le_i32_e32 vcc, v97, v219
	v_or_b32_e32 v97, 0xe2, v218
	s_nop 0
	v_cndmask_b32_e32 v66, v238, v66, vcc
	v_cmp_le_i32_e32 vcc, v97, v219
	v_or_b32_e32 v97, 0xc3, v218
	s_nop 0
	v_cndmask_b32_e32 v50, v238, v50, vcc
	v_cmp_le_i32_e32 vcc, v97, v219
	v_or_b32_e32 v97, 0xe3, v218
	s_nop 0
	v_cndmask_b32_e32 v67, v238, v67, vcc
	v_cmp_le_i32_e32 vcc, v97, v219
	v_or_b32_e32 v97, 0xc8, v218
	s_nop 0
	v_cndmask_b32_e32 v51, v238, v51, vcc
	v_cmp_le_i32_e32 vcc, v97, v219
	v_or_b32_e32 v97, 0xe8, v218
	s_nop 0
	v_cndmask_b32_e32 v68, v238, v68, vcc
	v_cmp_le_i32_e32 vcc, v97, v219
	v_or_b32_e32 v97, 0xc9, v218
	s_nop 0
	v_cndmask_b32_e32 v52, v238, v52, vcc
	v_cmp_le_i32_e32 vcc, v97, v219
	v_or_b32_e32 v97, 0xe9, v218
	s_nop 0
	v_cndmask_b32_e32 v69, v238, v69, vcc
	v_cmp_le_i32_e32 vcc, v97, v219
	v_or_b32_e32 v97, 0xca, v218
	s_nop 0
	v_cndmask_b32_e32 v53, v238, v53, vcc
	v_cmp_le_i32_e32 vcc, v97, v219
	v_or_b32_e32 v97, 0xea, v218
	s_nop 0
	v_cndmask_b32_e32 v70, v238, v70, vcc
	v_cmp_le_i32_e32 vcc, v97, v219
	v_or_b32_e32 v97, 0xcb, v218
	s_nop 0
	v_cndmask_b32_e32 v54, v238, v54, vcc
	v_cmp_le_i32_e32 vcc, v97, v219
	v_or_b32_e32 v97, 0xeb, v218
	s_nop 0
	v_cndmask_b32_e32 v71, v238, v71, vcc
	v_cmp_le_i32_e32 vcc, v97, v219
	v_or_b32_e32 v97, 0xd0, v218
	s_nop 0
	v_cndmask_b32_e32 v55, v238, v55, vcc
	v_cmp_le_i32_e32 vcc, v97, v219
	v_or_b32_e32 v97, 0xf0, v218
	s_nop 0
	v_cndmask_b32_e32 v72, v238, v72, vcc
	v_cmp_le_i32_e32 vcc, v97, v219
	v_or_b32_e32 v97, 0xd1, v218
	s_nop 0
	v_cndmask_b32_e32 v56, v238, v56, vcc
	v_cmp_le_i32_e32 vcc, v97, v219
	v_or_b32_e32 v97, 0xf1, v218
	s_nop 0
	v_cndmask_b32_e32 v73, v238, v73, vcc
	v_cmp_le_i32_e32 vcc, v97, v219
	v_or_b32_e32 v97, 0xd2, v218
	s_nop 0
	v_cndmask_b32_e32 v57, v238, v57, vcc
	v_cmp_le_i32_e32 vcc, v97, v219
	v_or_b32_e32 v97, 0xf2, v218
	s_nop 0
	v_cndmask_b32_e32 v74, v238, v74, vcc
	v_cmp_le_i32_e32 vcc, v97, v219
	v_or_b32_e32 v97, 0xd3, v218
	s_nop 0
	v_cndmask_b32_e32 v58, v238, v58, vcc
	v_cmp_le_i32_e32 vcc, v97, v219
	v_or_b32_e32 v97, 0xf3, v218
	s_nop 0
	v_cndmask_b32_e32 v75, v238, v75, vcc
	v_cmp_le_i32_e32 vcc, v97, v219
	v_or_b32_e32 v97, 0xd8, v218
	s_nop 0
	v_cndmask_b32_e32 v59, v238, v59, vcc
	v_cmp_le_i32_e32 vcc, v97, v219
	v_or_b32_e32 v97, 0xf8, v218
	s_nop 0
	v_cndmask_b32_e32 v76, v238, v76, vcc
	v_cmp_le_i32_e32 vcc, v97, v219
	v_or_b32_e32 v97, 0xd9, v218
	s_nop 0
	v_cndmask_b32_e32 v60, v238, v60, vcc
	v_cmp_le_i32_e32 vcc, v97, v219
	v_or_b32_e32 v97, 0xf9, v218
	s_nop 0
	v_cndmask_b32_e32 v77, v238, v77, vcc
	v_cmp_le_i32_e32 vcc, v97, v219
	v_or_b32_e32 v97, 0xda, v218
	s_nop 0
	v_cndmask_b32_e32 v61, v238, v61, vcc
	v_cmp_le_i32_e32 vcc, v97, v219
	v_or_b32_e32 v97, 0xfa, v218
	s_nop 0
	v_cndmask_b32_e32 v78, v238, v78, vcc
	v_cmp_le_i32_e32 vcc, v97, v219
	v_or_b32_e32 v97, 0xdb, v218
	s_nop 0
	v_cndmask_b32_e32 v62, v238, v62, vcc
	v_cmp_le_i32_e32 vcc, v97, v219
	v_or_b32_e32 v97, 0xfb, v218
	s_nop 0
	v_cndmask_b32_e32 v79, v238, v79, vcc
	v_cmp_le_i32_e32 vcc, v97, v219
	v_max_f32_e32 v97, v65, v65
	v_max_f32_e32 v97, v98, v97
	v_max3_f32 v98, v66, v67, v49
	v_max3_f32 v97, v97, v48, v50
	v_max3_f32 v97, v97, v51, v68
	v_max3_f32 v98, v98, v70, v71
	v_max3_f32 v97, v97, v69, v52
	v_max3_f32 v98, v98, v54, v55
	v_max3_f32 v97, v97, v53, v72
	v_max3_f32 v98, v98, v74, v75
	v_max3_f32 v97, v97, v73, v56
	v_max3_f32 v98, v98, v58, v59
	v_cndmask_b32_e32 v63, v238, v63, vcc
	v_max3_f32 v97, v97, v57, v76
	v_max3_f32 v98, v98, v78, v79
	v_max3_f32 v97, v97, v77, v60
	v_max3_f32 v98, v98, v62, v63
	v_max3_f32 v97, v97, v61, v98
	v_mov_b32_e32 v98, v97
	s_nop 1
	v_permlane32_swap_b32_e32 v97, v98
	v_max_f32_e32 v97, v97, v98
	v_cmp_lt_f32_e32 vcc, s47, v97
	s_cmp_lg_u64 vcc, 0
	s_cselect_b64 s[4:5], -1, 0
	s_cbranch_vccnz .LBB0_224

.LBB0_178:
	v_add_f32_e32 v205, v222, v32
	v_max_f32_e32 v32, v64, v65
	v_max3_f32 v33, v66, v67, v49
	v_max3_f32 v32, v32, v48, v50
	v_max3_f32 v32, v32, v51, v68
	v_max3_f32 v33, v33, v70, v71
	v_max3_f32 v32, v32, v69, v52
	v_max3_f32 v33, v33, v54, v55
	v_max3_f32 v32, v32, v53, v72
	v_max3_f32 v33, v33, v74, v75
	v_max3_f32 v32, v32, v73, v56
	v_max3_f32 v33, v33, v58, v59
	v_max3_f32 v32, v32, v57, v76
	v_max3_f32 v33, v33, v78, v79
	v_max3_f32 v32, v32, v77, v60
	v_max3_f32 v33, v33, v62, v63
	v_max3_f32 v32, v32, v61, v33
	v_mov_b32_e32 v33, v32
	s_nop 1
	v_permlane32_swap_b32_e32 v32, v33
	v_max_f32_e32 v32, v32, v33
	v_cmp_lt_f32_e32 vcc, s47, v32
	s_cmp_lg_u64 vcc, 0
	s_cselect_b64 s[52:53], -1, 0
	s_cbranch_vccnz .LBB0_218

.LBB0_189:
	v_add_f32_e32 v222, v205, v222
	v_max_f32_e32 v205, v80, v81
	v_max3_f32 v230, v82, v83, v33
	v_max3_f32 v205, v205, v32, v34
	v_max3_f32 v205, v205, v35, v84
	v_max3_f32 v230, v230, v86, v87
	v_max3_f32 v205, v205, v85, v36
	v_max3_f32 v230, v230, v38, v39
	v_max3_f32 v205, v205, v37, v88
	v_max3_f32 v230, v230, v90, v91
	v_max3_f32 v205, v205, v89, v40
	v_max3_f32 v230, v230, v42, v43
	v_max3_f32 v205, v205, v41, v92
	v_max3_f32 v230, v230, v94, v95
	v_max3_f32 v205, v205, v93, v44
	v_max3_f32 v230, v230, v46, v47
	v_max3_f32 v205, v205, v45, v230
	v_mov_b32_e32 v230, v205
	s_nop 1
	v_permlane32_swap_b32_e32 v205, v230
	v_max_f32_e32 v205, v205, v230
	v_cmp_lt_f32_e32 vcc, s47, v205
	s_cmp_lg_u64 vcc, 0
	s_cselect_b64 s[70:71], -1, 0
	s_cbranch_vccnz .LBB0_221
	v_cndmask_b32_e64 v205, 0, 1, s[16:17]
	v_cmp_ne_u32_e64 s[4:5], 1, v205
	s_andn2_b64 vcc, exec, s[16:17]
	s_cbranch_vccnz .LBB0_192
